# P2: a dilated-branch item that continues the previous item's residue sequence takes its first 128 K/V rows from the previous item's LDS rows 256..383 instead of reloading them from global memory
# speedup vs baseline: 1.0011x; 1.0011x over previous
; #define LAS __attribute__((address_space(3)))
; #define ATT_QPTR(I, i_) (Z + ((size_t)((I).qslot0() + ((I).isA ? ((wave * 4 + (i_)) >> 3) : 0)) * TT + (I).seq0 + (I).res * (I).Lr + (I).j0 + 16 * ATT_QT(I, i_) + qi) * 64)
;     int tid_l = threadIdx.x; asm volatile("" : "+v"(tid_l));
;     const int tid = tid_l, lane = tid & 63, wave = __builtin_amdgcn_readfirstlane(tid >> 6), qi = lane & 15, g = lane >> 4;
;     LAS unsigned char* ldsK = lds + L_K; LAS unsigned char* ldsV = lds + L_V; LAS float* tbl = (LAS float*)(lds + L_T); LAS float* pmt = (LAS float*)(lds + L_PM);
;     const int G = gridDim.x, bx = blockIdx.x;
;     const int na0 = (int)((long)bx * NITEM_A / G), nA = (int)((long)(bx + 1) * NITEM_A / G) - na0;
;     const int nb0 = (int)((long)bx * NITEM_B / G), nB = (int)((long)(bx + 1) * NITEM_B / G) - nb0;
;     const int nloc = nA + nB, r0 = tid >> 3, ch = tid & 7;
;     v4u pk[6], pv[6];
;     ...
;     if (nloc <= 0) return;
;     Item cur = decode(0, na0, nA, nb0), nxt = cur;
;     ...
;     bf16x8 q0, q1;
;     { const bf16* qp = ATT_QPTR(cur, 0); q0 = *(const bf16x8*)(qp + g * 8); q1 = *(const bf16x8*)(qp + 32 + g * 8); }
;     asm volatile("" ::: "memory");
;     ATT_ISSUE(cur);
;     int tkey = -1;
.LBB0_178:
	s_or_b64 exec, exec, s[8:9]
	v_lshlrev_b32_e32 v0, 3, v144
	v_and_b32_e32 v0, 24, v0
	v_mov_b32_e32 v63, v21
	s_movk_i32 s78, 0x90
	s_movk_i32 s79, 0xa0
	v_lshl_add_u32 v175, v117, 4, 0
	v_lshlrev_b32_e32 v148, 2, v116
	v_add_u32_e32 v150, 0, v0
	v_lshl_add_u64 v[152:153], s[20:21], 0, v[62:63]
	v_mul_lo_u32 v0, v151, s78
	v_mul_lo_u32 v63, v151, s79
	s_add_i32 s0, 0, 0x1f000
	v_add_u32_e32 v180, 64, v151
	v_add_u32_e32 v1, 0x2800, v63
	v_add_u32_e32 v182, 0x80, v151
	v_add_u32_e32 v2, 0x5000, v63
	v_add_u32_e32 v184, 0xc0, v151
	v_add_u32_e32 v3, 0x7800, v63
	v_add_u32_e32 v186, 0x100, v151
	v_add_u32_e32 v4, 0xa000, v63
	v_add_u32_e32 v188, 0x140, v151
	v_add_u32_e32 v5, 0xc800, v63
	v_sub_u32_e32 v6, v148, v144
	v_add_u32_e32 v242, 4, v151
	v_bfe_u32 v242, v242, 3, 1
	v_xor_b32_e32 v242, v242, v117
	v_lshl_add_u32 v193, v242, 4, v0
	v_mbcnt_lo_u32_b32 v0, -1, 0
	v_mov_b32_e32 v145, v16
	v_cmp_ne_u32_e64 s[8:9], 0, v117
	s_lshl_b32 s77, s49, 2
	v_add_u32_e32 v243, 4, v144
	v_bfe_u32 v243, v243, 3, 1
	v_xor_b32_e32 v243, v243, v116
	v_lshlrev_b32_e32 v146, 4, v243
	v_and_b32_e32 v253, 1, v144
	v_mul_u32_u24_e32 v253, 0x3884, v253
	v_lshrrev_b32_e32 v178, 2, v144
	v_mov_b32_e32 v149, v21
	v_cmp_eq_u32_e64 s[4:5], 0, v116
	v_lshl_add_u32 v179, v151, 2, s0
	v_lshl_add_u32 v181, v180, 2, s0
	v_lshl_add_u32 v183, v182, 2, s0
	v_lshl_add_u32 v185, v184, 2, s0
	v_lshl_add_u32 v187, v186, 2, s0
	v_lshl_add_u32 v189, v188, 2, s0
	s_lshl_b32 s80, s49, 1
	v_subrev_u32_e32 v190, s73, v6
	s_mov_b32 s66, -1
	s_mov_b32 s81, 0xff800000
	v_add_u32_e32 v191, v175, v2
	v_add_u32_e32 v192, v175, v4
	s_movk_i32 s82, 0x280
	s_add_i32 s83, 0, 0x1c800
	v_add_u32_e32 v194, v175, v1
	v_mov_b32_e32 v195, 0xff800000
	v_add_u32_e32 v197, v175, v3
	v_add_u32_e32 v198, v175, v5
	v_mov_b32_e32 v56, 0
	v_mbcnt_hi_u32_b32 v199, -1, v0
	v_mov_b32_e32 v200, 0x42000000
	s_mov_b32 s84, 0
	v_mov_b32_e32 v240, 0
	s_branch .LBB0_180

; #define LAS __attribute__((address_space(3)))
;     ...
;         __syncthreads();
; #pragma unroll
;         for (int i = 0; i < 6; ++i) { const int row = r0 + 64 * i; *(LAS v4u*)(ldsK + row * KRS + ch * 16) = pk[i]; *(LAS v4u*)(ldsV + row * VRS + ch * 16) = pv[i];
.LBB0_180:
	s_cmp_lg_u32 s70, 0
	s_cselect_b64 s[48:49], -1, 0
	s_cmp_eq_u32 s70, 0
	s_cselect_b64 s[50:51], -1, 0
	s_and_b64 s[0:1], s[50:51], exec
	s_movk_i32 s0, 0xffc0
	s_cselect_b32 s0, s0, 0xffffff80
	s_cmp_lg_u32 s75, 0
	s_cselect_b64 s[54:55], -1, 0
	s_cmp_eq_u32 s75, 0
	s_cselect_b64 s[6:7], -1, 0
	s_and_b64 s[56:57], s[6:7], exec
	s_cselect_b32 s58, s74, s98
	v_add_u32_e32 v0, v175, v63
	s_barrier
	v_readlane_b32 vcc_lo, v240, 0
	s_nop 1
	s_cmp_eq_u32 vcc_lo, 0
	s_cbranch_scc1 .Lmy_nocopy
	ds_read_b128 v[24:27], v193 offset:36864
	ds_read_b128 v[28:31], v193 offset:46080
	ds_read_b128 v[92:95], v192 offset:55296
	ds_read_b128 v[96:99], v198 offset:55296
	s_waitcnt lgkmcnt(0)
.Lmy_nocopy:
	ds_write_b128 v193, v[24:27]
	s_waitcnt vmcnt(0)
	ds_write_b128 v0, v[92:95] offset:55296
	s_and_saveexec_b64 s[56:57], s[8:9]
	s_xor_b64 s[56:57], exec, s[56:57]
	s_cbranch_execz .LBB0_182
	ds_write_b128 v193, v[28:31] offset:9216
	ds_write_b128 v194, v[96:99] offset:55296

; __device__ __forceinline__ Item decode(int k, int na0, int nA, int nb0) {
;     Item I; int tok0;
;     if (k < nA) { const int ia = na0 + k; I.isA = 1; I.hs = ia / (TT / 128); tok0 = (ia % (TT / 128)) * 128; I.dil = 1; }
;     else { const int ib = nb0 + (k - nA); I.hs = ib / (TT / 256); I.isA = 0; const int gi = I.hs >> 2; tok0 = (ib % (TT / 256)) * 256; I.dil = gi == 0 ? 1 : (gi == 1 ? 4 : 16); }
;     int L;
;     if (tok0 < TP) { L = 2048; I.seq0 = (tok0 / 2048) * 2048; } else { L = 8192; I.seq0 = TP + ((tok0 - TP) / 8192) * 8192; }
;     I.res = 0; I.j0 = tok0 - I.seq0; I.Lr = L; I.Lre = L; I.pair = 0;
;     if (!I.isA) { I.Lr = L / I.dil; const int blk = (tok0 - I.seq0) / 256;
;         if (I.Lr >= 256) { const int bpr = I.Lr / 256; I.res = blk / bpr; I.j0 = (blk % bpr) * 256; I.Lre = I.Lr; }
;         else { I.res = 2 * blk; I.j0 = 0; I.Lre = 2 * I.Lr; I.pair = 1; } }
;     return I;
;     ...
;         if (more) { nxt = decode(k + 1, na0, nA, nb0); ATT_ISSUE(nxt); }
.LBB0_225:
	s_mul_i32 s65, s87, s85
	s_add_i32 s1, s1, s67
	s_add_i32 s58, s86, s58
	s_add_i32 s88, s65, s69
	s_mul_hi_i32 s59, s1, 0xa00000
	s_mul_i32 s1, s1, 0xa00000
	v_add_u32_e32 v20, s58, v151
	s_add_u32 s58, s28, s1
	s_addc_u32 s59, s29, s59
	s_add_i32 s0, s0, s67
	s_mul_hi_i32 s1, s0, 0xa00000
	s_mul_i32 s0, s0, 0xa00000
	s_add_u32 s60, s28, s0
	s_addc_u32 s61, s29, s1
	v_mov_b32_e32 v57, v56
	v_mov_b64_e32 v[24:25], v[56:57]
	v_mov_b64_e32 v[26:27], v[56:57]
	v_mov_b64_e32 v[28:29], v[56:57]
	v_mov_b64_e32 v[30:31], v[56:57]
	v_mov_b64_e32 v[32:33], v[56:57]
	v_mov_b64_e32 v[34:35], v[56:57]
	v_mov_b64_e32 v[36:37], v[56:57]
	v_mov_b64_e32 v[38:39], v[56:57]
	v_mov_b64_e32 v[40:41], v[56:57]
	v_mov_b64_e32 v[42:43], v[56:57]
	v_mov_b64_e32 v[44:45], v[56:57]
	v_mov_b64_e32 v[46:47], v[56:57]
	v_mov_b64_e32 v[92:93], v[56:57]
	v_mov_b64_e32 v[94:95], v[56:57]
	v_mov_b64_e32 v[96:97], v[56:57]
	v_mov_b64_e32 v[98:99], v[56:57]
	v_mov_b64_e32 v[100:101], v[56:57]
	v_mov_b64_e32 v[102:103], v[56:57]
	v_mov_b64_e32 v[104:105], v[56:57]
	v_mov_b64_e32 v[106:107], v[56:57]
	v_mov_b64_e32 v[64:65], v[56:57]
	v_mov_b64_e32 v[66:67], v[56:57]
	v_mov_b32_e32 v58, v56
	v_mov_b32_e32 v59, v56
	v_mov_b32_e32 v60, v56
	v_mov_b32_e32 v61, v56
	s_mov_b32 s62, 0
	s_cmp_lg_u32 s70, 0
	s_cbranch_scc1 .Lmy_nocont
	s_and_b64 vcc, exec, s[48:49]
	s_cbranch_vccnz .Lmy_nocont
	s_cmp_lg_u32 s67, s46
	s_cbranch_scc1 .Lmy_nocont
	s_cmp_lg_u32 s69, s97
	s_cbranch_scc1 .Lmy_nocont
	s_cmp_lg_u32 s87, s92
	s_cbranch_scc1 .Lmy_nocont
	s_cmp_lg_u32 s85, s98
	s_cbranch_scc1 .Lmy_nocont
	s_add_i32 s63, s99, 0x100
	s_cmp_lg_u32 s86, s63
	s_cbranch_scc1 .Lmy_nocont
	s_mov_b32 s62, 1
.Lmy_nocont:
	v_writelane_b32 v240, s62, 0
	s_cmp_lg_u32 s62, 0
	s_cbranch_scc1 .Lmy_iss_1b
	v_cmp_gt_u32_e32 vcc, s74, v20
	s_and_saveexec_b64 s[62:63], vcc
	s_cbranch_execz .Lmy_iss_0
	v_add_u32_e32 v0, s88, v20
	v_ashrrev_i32_e32 v1, 31, v0
	v_lshlrev_b64 v[0:1], 7, v[0:1]
	v_lshl_or_b32 v0, v174, 1, v0
	v_lshl_add_u64 v[2:3], s[60:61], 0, v[0:1]
	v_lshl_add_u64 v[0:1], s[58:59], 0, v[0:1]
	global_load_dwordx4 v[24:27], v[0:1], off
	global_load_dwordx4 v[92:95], v[2:3], off

.Lmy_iss_1b:
	v_add_u32_e32 v22, 0x80, v20
	v_cmp_gt_u32_e32 vcc, s74, v22
	s_and_saveexec_b64 s[62:63], vcc
	s_cbranch_execz .Lmy_iss_2
	v_add_u32_e32 v0, s88, v22
	v_ashrrev_i32_e32 v1, 31, v0
	v_lshlrev_b64 v[0:1], 7, v[0:1]
	v_lshl_or_b32 v0, v174, 1, v0
	v_lshl_add_u64 v[2:3], s[60:61], 0, v[0:1]
	v_lshl_add_u64 v[0:1], s[58:59], 0, v[0:1]
	global_load_dwordx4 v[32:35], v[0:1], off
	global_load_dwordx4 v[100:103], v[2:3], off
